# deferred weight conversion rebalanced: phase 0 converts only layer 0 gate/up needed first; each layer's remaining weights in its own G1 idle tails
# speedup vs baseline: 1.0122x; 1.0122x over previous
; __device__ __forceinline__ void prologue_a(const Args& a, LAS unsigned char* lds, int tid, int G) {
;     ...
;         const int gw = blockIdx.x * 8 + wave, NGW = G * 8;
;         constexpr int PER_L = 10240;
;         for (int it = gw; it < DEPTH * PER_L; it += NGW) {
.LBB0_26:
	s_and_b64 vcc, exec, s[8:9]
	s_cbranch_vccz .LBB0_600
	s_mov_b32 s100, s99
	s_mov_b32 s101, s98
	s_movk_i32 s32, 0x1080

; #define PG8_WAIT_V(n) asm volatile("s_waitcnt vmcnt(" #n ")" ::: "memory")
; #define PG8_BAR __builtin_amdgcn_s_barrier()
; template <class Epi, class Sched, bool ALIGN_EPI = false, bool SP2 = false>
; __device__ __forceinline__ void gemm_phase(LAS unsigned char* lds, const Gemm g, const Sched& S, const Epi& E, const int tid) {
;     ...
;     PG8_WAIT_V(0);
;     if constexpr (!ALIGN_EPI) { if (wr == 0) PG8_BAR; }
;     PG8_BAR;
; __global__ void __launch_bounds__(512, 2) mega_fwd(Args a) {
;     ...
;             const int q = p - 2, l = q / 10, st = q % 10; const bool last = (l == DEPTH - 1);
;             const int Mfull = TT, Mlate = last ? T_LAT : TT;
;             if (st == 0 || st == 7) {
;                 const int sub = (st == 7), M = sub ? Mlate : Mfull;
;                 pg8::Gemm g{(const bf16_t*)(ws + WS_Y), (const bf16_t*)(ws + WS_WGU) + (size_t)(l * 2 + sub) * NGU * DM, M, NGU, DM};
;                 pg8::StaticOrder S; S.init(M, NGU, G, (int)blockIdx.x); S.nkt = DM / pg8::BK;
;                 pg8::EpiSwiGLU E{(bf16_t*)(ws + WS_R1)};
;                 pg8::gemm_phase<pg8::EpiSwiGLU, pg8::StaticOrder, true, true>(lds, g, S, E, tid);
.LBB0_598:
	s_waitcnt vmcnt(0)
	v_readlane_b32 s22, v254, 35
	v_readlane_b32 s24, v254, 37
	v_readlane_b32 s0, v254, 39
	v_readlane_b32 s60, v254, 41
	v_readlane_b32 s28, v254, 43
	v_readlane_b32 s20, v254, 45
	s_barrier
	v_readlane_b32 s23, v254, 36
	v_readlane_b32 s25, v254, 38
	v_readlane_b32 s1, v254, 40
	s_mov_b32 s26, s0
	v_readlane_b32 s61, v254, 42
	v_readlane_b32 s29, v254, 44
	v_readlane_b32 s21, v254, 46
	s_add_i32 s8, s6, -2
	s_mul_hi_u32 s9, s8, 0xcccccccd
	s_lshr_b32 s9, s9, 3
	s_mul_i32 s10, s9, 10
	s_sub_i32 s10, s8, s10
	s_cmp_lt_u32 s2, 48
	s_cbranch_scc1 .Ldef_skip
	s_cmp_eq_u32 s10, 7
	s_cbranch_scc1 .Ldef_st7
	s_mul_i32 s9, s9, 0x2800
	s_add_i32 s32, s9, 0x2800
	s_add_i32 s9, s9, 0x1080
	s_branch .Ldef_go
.Ldef_st7:
	s_cmp_gt_u32 s9, 2
	s_cbranch_scc1 .Ldef_skip
	s_add_i32 s9, s9, 1
	s_mul_i32 s9, s9, 0x2800
	s_add_i32 s32, s9, 0x1080
.Ldef_go:
	s_add_i32 s100, s9, s99
	s_add_i32 s100, s100, 0xfffffe80
	s_movk_i32 s101, 0x680
	s_branch .Ldef_entry
